# k16 with SwiGLU epilogue using one v_rcp per pair of outputs (1/a = b*rcp(a*b)), f32, 12 instead of 16 transcendentals per row group
# baseline (speedup 1.0000x reference)
; __device__ __forceinline__ unsigned cvtpk(float lo, float hi) { f32x2_t v = {lo, hi}; bf16x2_t b = __builtin_convertvector(v, bf16x2_t); return __builtin_bit_cast(unsigned, b); }
;     __device__ __forceinline__ void operator()(const f32x4 (&acc)[2][2][4][2], const Unit& u, int wr, int wc, int fr, int fq) const {
;         const int row0 = u.pm * BM + wr * 64 + fr, col0 = u.pn * 128 + wc * 32 + 8 * fq;
; #pragma unroll
;         for (int ai = 0; ai < 2; ++ai)
; #pragma unroll
;             for (int m = 0; m < 4; ++m) {
;                 const int row = row0 + ai * HALF + m * 16;
;                 const float rs = 1.0f / sqrtf(ssq_sum(ssq + (size_t)row * 16) * (1.0f / DM) + EPS);
;                 float hv[8];
; #pragma unroll
;                 for (int n = 0; n < 2; ++n)
; #pragma unroll
;                     for (int e = 0; e < 4; ++e) {
;                         const float gg = acc[ai][0][m][n][e] * rs, uu = acc[ai][1][m][n][e] * rs;
;                         const float den = 1.0f + __builtin_amdgcn_exp2f(-gg * LOG2E);
;                         hv[n * 4 + e] = gg * uu * __builtin_amdgcn_rcpf(den);
;                     }
;                 u32x4 w; w.x = cvtpk(hv[0], hv[1]); w.y = cvtpk(hv[2], hv[3]); w.z = cvtpk(hv[4], hv[5]); w.w = cvtpk(hv[6], hv[7]);
;                 *(u32x4*)(H + (size_t)row * DFF + col0) = w;
.LBB0_244:
	v_readlane_b32 s9, v254, 7
	v_mbcnt_lo_u32_b32 v144, -1, 0
	v_mbcnt_hi_u32_b32 v144, -1, v144
	v_lshrrev_b32_e32 v145, 1, v144
	v_lshl_add_u32 v145, s9, 5, v145
	v_and_b32_e32 v146, 1, v144
	v_lshl_add_u32 v147, s8, 8, v145
	v_lshlrev_b32_e32 v147, 6, v147
	v_lshl_add_u32 v147, v146, 5, v147
	global_load_dwordx4 v[160:163], v147, s[14:15]
	global_load_dwordx4 v[164:167], v147, s[14:15] offset:16
	v_lshl_add_u32 v148, s8, 8, v152
	v_mov_b64_e32 v[146:147], s[16:17]
	v_mad_i64_i32 v[176:177], s[8:9], v148, s56, v[146:147]
	v_lshl_or_b32 v150, s2, 7, v154
	v_mov_b32_e32 v151, 0
	v_lshlrev_b64 v[150:151], 1, v[150:151]
	v_lshl_add_u64 v[176:177], v[176:177], 0, v[150:151]
	v_lshlrev_b32_e32 v145, 3, v145
	v_add_u32_e32 v145, 0x20100, v145
	v_lshlrev_b32_e32 v146, 3, v152
	v_add_u32_e32 v146, 0x20100, v146
	s_mov_b32 s9, 0
	s_waitcnt vmcnt(0)
	v_pk_add_f32 v[160:161], v[160:161], v[162:163]
	v_pk_add_f32 v[164:165], v[164:165], v[166:167]
	v_pk_add_f32 v[160:161], v[160:161], v[164:165]
	v_add_f32_e32 v160, v160, v161
	s_nop 1
	v_add_f32_dpp v160, v160, v160 quad_perm:[1,0,3,2] row_mask:0xf bank_mask:0xf
	v_fmamk_f32 v160, v160, 0x3a800000, v158
	v_rsq_f32_e32 v161, v160
	s_nop 0
	v_mul_f32_e32 v161, 0xbfb8aa3b, v161
	ds_write_b64 v145, v[160:161]
	s_waitcnt lgkmcnt(0)
	s_barrier
	ds_read_b64 v[160:161], v146 offset:0
	ds_read_b64 v[162:163], v146 offset:128
	ds_read_b64 v[164:165], v146 offset:256
	ds_read_b64 v[166:167], v146 offset:384
	ds_read_b64 v[168:169], v146 offset:1024
	ds_read_b64 v[170:171], v146 offset:1152
	ds_read_b64 v[172:173], v146 offset:1280
	ds_read_b64 v[174:175], v146 offset:1408
	v_pk_mul_f32 v[116:117], v[124:125], v[116:117]
	v_pk_mul_f32 v[118:119], v[126:127], v[118:119]
	v_pk_mul_f32 v[112:113], v[120:121], v[112:113]
	v_pk_mul_f32 v[114:115], v[122:123], v[114:115]
	s_waitcnt lgkmcnt(7)
	v_mov_b32_e32 v150, v161
	v_pk_mul_f32 v[124:125], v[124:125], v[150:151] op_sel_hi:[1,0]
	v_pk_mul_f32 v[126:127], v[126:127], v[150:151] op_sel_hi:[1,0]
	v_pk_mul_f32 v[120:121], v[120:121], v[150:151] op_sel_hi:[1,0]
	v_pk_mul_f32 v[122:123], v[122:123], v[150:151] op_sel_hi:[1,0]
	v_exp_f32_e32 v124, v124
	v_exp_f32_e32 v125, v125
	v_exp_f32_e32 v126, v126
	v_exp_f32_e32 v127, v127
	v_exp_f32_e32 v120, v120
	v_exp_f32_e32 v121, v121
	v_exp_f32_e32 v122, v122
	v_exp_f32_e32 v123, v123
	v_fma_f32 v124, v124, v160, v160
	v_fma_f32 v125, v125, v160, v160
	v_fma_f32 v126, v126, v160, v160
	v_fma_f32 v127, v127, v160, v160
	v_fma_f32 v120, v120, v160, v160
	v_fma_f32 v121, v121, v160, v160
	v_fma_f32 v122, v122, v160, v160
	v_fma_f32 v123, v123, v160, v160
	v_mul_f32_e32 v144, v124, v125
	v_mul_f32_e32 v146, v126, v127
	v_mul_f32_e32 v148, v120, v121
	v_mul_f32_e32 v150, v122, v123
	v_rcp_f32_e32 v144, v144
	v_rcp_f32_e32 v146, v146
	v_rcp_f32_e32 v148, v148
	v_rcp_f32_e32 v150, v150
	v_pk_mul_f32 v[116:117], v[116:117], v[124:125] op_sel:[0,1] op_sel_hi:[1,0]
	v_pk_mul_f32 v[118:119], v[118:119], v[126:127] op_sel:[0,1] op_sel_hi:[1,0]
	v_pk_mul_f32 v[112:113], v[112:113], v[120:121] op_sel:[0,1] op_sel_hi:[1,0]
	v_pk_mul_f32 v[114:115], v[114:115], v[122:123] op_sel:[0,1] op_sel_hi:[1,0]
	v_pk_mul_f32 v[116:117], v[116:117], v[144:145] op_sel_hi:[1,0]
	v_pk_mul_f32 v[118:119], v[118:119], v[146:147] op_sel_hi:[1,0]
	v_pk_mul_f32 v[112:113], v[112:113], v[148:149] op_sel_hi:[1,0]
	v_pk_mul_f32 v[114:115], v[114:115], v[150:151] op_sel_hi:[1,0]
	v_cvt_pk_bf16_f32 v124, v116, v117
	v_cvt_pk_bf16_f32 v125, v118, v119
	v_cvt_pk_bf16_f32 v126, v112, v113
	v_cvt_pk_bf16_f32 v127, v114, v115
	global_store_dwordx4 v[176:177], v[124:127], off
	v_pk_mul_f32 v[100:101], v[108:109], v[100:101]
	v_pk_mul_f32 v[102:103], v[110:111], v[102:103]
	v_pk_mul_f32 v[96:97], v[104:105], v[96:97]
	v_pk_mul_f32 v[98:99], v[106:107], v[98:99]
	s_waitcnt lgkmcnt(6)
	v_mov_b32_e32 v150, v163
	v_pk_mul_f32 v[108:109], v[108:109], v[150:151] op_sel_hi:[1,0]
	v_pk_mul_f32 v[110:111], v[110:111], v[150:151] op_sel_hi:[1,0]
	v_pk_mul_f32 v[104:105], v[104:105], v[150:151] op_sel_hi:[1,0]
	v_pk_mul_f32 v[106:107], v[106:107], v[150:151] op_sel_hi:[1,0]
	v_exp_f32_e32 v108, v108
	v_exp_f32_e32 v109, v109
	v_exp_f32_e32 v110, v110
	v_exp_f32_e32 v111, v111
	v_exp_f32_e32 v104, v104
	v_exp_f32_e32 v105, v105
	v_exp_f32_e32 v106, v106
	v_exp_f32_e32 v107, v107
	v_fma_f32 v108, v108, v162, v162
	v_fma_f32 v109, v109, v162, v162
	v_fma_f32 v110, v110, v162, v162
	v_fma_f32 v111, v111, v162, v162
	v_fma_f32 v104, v104, v162, v162
	v_fma_f32 v105, v105, v162, v162
	v_fma_f32 v106, v106, v162, v162
	v_fma_f32 v107, v107, v162, v162
	v_mul_f32_e32 v144, v108, v109
	v_mul_f32_e32 v146, v110, v111
	v_mul_f32_e32 v148, v104, v105
	v_mul_f32_e32 v150, v106, v107
	v_rcp_f32_e32 v144, v144
	v_rcp_f32_e32 v146, v146
	v_rcp_f32_e32 v148, v148
	v_rcp_f32_e32 v150, v150
	s_mov_b32 s8, 0x16000
	v_pk_mul_f32 v[100:101], v[100:101], v[108:109] op_sel:[0,1] op_sel_hi:[1,0]
	v_pk_mul_f32 v[102:103], v[102:103], v[110:111] op_sel:[0,1] op_sel_hi:[1,0]
	v_pk_mul_f32 v[96:97], v[96:97], v[104:105] op_sel:[0,1] op_sel_hi:[1,0]
	v_pk_mul_f32 v[98:99], v[98:99], v[106:107] op_sel:[0,1] op_sel_hi:[1,0]
	v_pk_mul_f32 v[100:101], v[100:101], v[144:145] op_sel_hi:[1,0]
	v_pk_mul_f32 v[102:103], v[102:103], v[146:147] op_sel_hi:[1,0]
	v_pk_mul_f32 v[96:97], v[96:97], v[148:149] op_sel_hi:[1,0]
	v_pk_mul_f32 v[98:99], v[98:99], v[150:151] op_sel_hi:[1,0]
	v_cvt_pk_bf16_f32 v108, v100, v101
	v_cvt_pk_bf16_f32 v109, v102, v103
	v_cvt_pk_bf16_f32 v110, v96, v97
	v_cvt_pk_bf16_f32 v111, v98, v99
	v_lshl_add_u64 v[178:179], v[176:177], 0, s[8:9]
	global_store_dwordx4 v[178:179], v[108:111], off
	v_pk_mul_f32 v[84:85], v[92:93], v[84:85]
	v_pk_mul_f32 v[86:87], v[94:95], v[86:87]
	v_pk_mul_f32 v[80:81], v[88:89], v[80:81]
	v_pk_mul_f32 v[82:83], v[90:91], v[82:83]
	s_waitcnt lgkmcnt(5)
; __device__ __forceinline__ unsigned cvtpk(float lo, float hi) { f32x2_t v = {lo, hi}; bf16x2_t b = __builtin_convertvector(v, bf16x2_t); return __builtin_bit_cast(unsigned, b); }
;     __device__ __forceinline__ void operator()(const f32x4 (&acc)[2][2][4][2], const Unit& u, int wr, int wc, int fr, int fq) const {
;     ...
;             for (int m = 0; m < 4; ++m) {
;                 const int row = row0 + ai * HALF + m * 16;
;                 const float rs = 1.0f / sqrtf(ssq_sum(ssq + (size_t)row * 16) * (1.0f / DM) + EPS);
;                 float hv[8];
; #pragma unroll
;                 for (int n = 0; n < 2; ++n)
; #pragma unroll
;                     for (int e = 0; e < 4; ++e) {
;                         const float gg = acc[ai][0][m][n][e] * rs, uu = acc[ai][1][m][n][e] * rs;
;                         const float den = 1.0f + __builtin_amdgcn_exp2f(-gg * LOG2E);
;                         hv[n * 4 + e] = gg * uu * __builtin_amdgcn_rcpf(den);
;                     }
;                 u32x4 w; w.x = cvtpk(hv[0], hv[1]); w.y = cvtpk(hv[2], hv[3]); w.z = cvtpk(hv[4], hv[5]); w.w = cvtpk(hv[6], hv[7]);
;                 *(u32x4*)(H + (size_t)row * DFF + col0) = w;
	v_mov_b32_e32 v150, v165
	v_pk_mul_f32 v[92:93], v[92:93], v[150:151] op_sel_hi:[1,0]
	v_pk_mul_f32 v[94:95], v[94:95], v[150:151] op_sel_hi:[1,0]
	v_pk_mul_f32 v[88:89], v[88:89], v[150:151] op_sel_hi:[1,0]
	v_pk_mul_f32 v[90:91], v[90:91], v[150:151] op_sel_hi:[1,0]
	v_exp_f32_e32 v92, v92
	v_exp_f32_e32 v93, v93
	v_exp_f32_e32 v94, v94
	v_exp_f32_e32 v95, v95
	v_exp_f32_e32 v88, v88
	v_exp_f32_e32 v89, v89
	v_exp_f32_e32 v90, v90
	v_exp_f32_e32 v91, v91
	v_fma_f32 v92, v92, v164, v164
	v_fma_f32 v93, v93, v164, v164
	v_fma_f32 v94, v94, v164, v164
	v_fma_f32 v95, v95, v164, v164
	v_fma_f32 v88, v88, v164, v164
	v_fma_f32 v89, v89, v164, v164
	v_fma_f32 v90, v90, v164, v164
	v_fma_f32 v91, v91, v164, v164
	v_mul_f32_e32 v144, v92, v93
	v_mul_f32_e32 v146, v94, v95
	v_mul_f32_e32 v148, v88, v89
	v_mul_f32_e32 v150, v90, v91
	v_rcp_f32_e32 v144, v144
	v_rcp_f32_e32 v146, v146
	v_rcp_f32_e32 v148, v148
	v_rcp_f32_e32 v150, v150
	s_mov_b32 s8, 0x2c000
	v_pk_mul_f32 v[84:85], v[84:85], v[92:93] op_sel:[0,1] op_sel_hi:[1,0]
	v_pk_mul_f32 v[86:87], v[86:87], v[94:95] op_sel:[0,1] op_sel_hi:[1,0]
	v_pk_mul_f32 v[80:81], v[80:81], v[88:89] op_sel:[0,1] op_sel_hi:[1,0]
	v_pk_mul_f32 v[82:83], v[82:83], v[90:91] op_sel:[0,1] op_sel_hi:[1,0]
	v_pk_mul_f32 v[84:85], v[84:85], v[144:145] op_sel_hi:[1,0]
	v_pk_mul_f32 v[86:87], v[86:87], v[146:147] op_sel_hi:[1,0]
	v_pk_mul_f32 v[80:81], v[80:81], v[148:149] op_sel_hi:[1,0]
	v_pk_mul_f32 v[82:83], v[82:83], v[150:151] op_sel_hi:[1,0]
	v_cvt_pk_bf16_f32 v92, v84, v85
	v_cvt_pk_bf16_f32 v93, v86, v87
	v_cvt_pk_bf16_f32 v94, v80, v81
	v_cvt_pk_bf16_f32 v95, v82, v83
	v_lshl_add_u64 v[178:179], v[176:177], 0, s[8:9]
	global_store_dwordx4 v[178:179], v[92:95], off
	v_pk_mul_f32 v[68:69], v[76:77], v[68:69]
	v_pk_mul_f32 v[70:71], v[78:79], v[70:71]
	v_pk_mul_f32 v[64:65], v[72:73], v[64:65]
	v_pk_mul_f32 v[66:67], v[74:75], v[66:67]
	s_waitcnt lgkmcnt(4)
	v_mov_b32_e32 v150, v167
	v_pk_mul_f32 v[76:77], v[76:77], v[150:151] op_sel_hi:[1,0]
	v_pk_mul_f32 v[78:79], v[78:79], v[150:151] op_sel_hi:[1,0]
	v_pk_mul_f32 v[72:73], v[72:73], v[150:151] op_sel_hi:[1,0]
	v_pk_mul_f32 v[74:75], v[74:75], v[150:151] op_sel_hi:[1,0]
	v_exp_f32_e32 v76, v76
	v_exp_f32_e32 v77, v77
	v_exp_f32_e32 v78, v78
	v_exp_f32_e32 v79, v79
	v_exp_f32_e32 v72, v72
	v_exp_f32_e32 v73, v73
	v_exp_f32_e32 v74, v74
	v_exp_f32_e32 v75, v75
	v_fma_f32 v76, v76, v166, v166
	v_fma_f32 v77, v77, v166, v166
	v_fma_f32 v78, v78, v166, v166
	v_fma_f32 v79, v79, v166, v166
	v_fma_f32 v72, v72, v166, v166
	v_fma_f32 v73, v73, v166, v166
	v_fma_f32 v74, v74, v166, v166
	v_fma_f32 v75, v75, v166, v166
	v_mul_f32_e32 v144, v76, v77
	v_mul_f32_e32 v146, v78, v79
	v_mul_f32_e32 v148, v72, v73
	v_mul_f32_e32 v150, v74, v75
	v_rcp_f32_e32 v144, v144
	v_rcp_f32_e32 v146, v146
	v_rcp_f32_e32 v148, v148
	v_rcp_f32_e32 v150, v150
	s_mov_b32 s8, 0x42000
	v_pk_mul_f32 v[68:69], v[68:69], v[76:77] op_sel:[0,1] op_sel_hi:[1,0]
	v_pk_mul_f32 v[70:71], v[70:71], v[78:79] op_sel:[0,1] op_sel_hi:[1,0]
	v_pk_mul_f32 v[64:65], v[64:65], v[72:73] op_sel:[0,1] op_sel_hi:[1,0]
	v_pk_mul_f32 v[66:67], v[66:67], v[74:75] op_sel:[0,1] op_sel_hi:[1,0]
	v_pk_mul_f32 v[68:69], v[68:69], v[144:145] op_sel_hi:[1,0]
	v_pk_mul_f32 v[70:71], v[70:71], v[146:147] op_sel_hi:[1,0]
	v_pk_mul_f32 v[64:65], v[64:65], v[148:149] op_sel_hi:[1,0]
	v_pk_mul_f32 v[66:67], v[66:67], v[150:151] op_sel_hi:[1,0]
	v_cvt_pk_bf16_f32 v76, v68, v69
	v_cvt_pk_bf16_f32 v77, v70, v71
	v_cvt_pk_bf16_f32 v78, v64, v65
	v_cvt_pk_bf16_f32 v79, v66, v67
	v_lshl_add_u64 v[178:179], v[176:177], 0, s[8:9]
	global_store_dwordx4 v[178:179], v[76:79], off
	v_pk_mul_f32 v[52:53], v[60:61], v[52:53]
	v_pk_mul_f32 v[54:55], v[62:63], v[54:55]
	v_pk_mul_f32 v[48:49], v[56:57], v[48:49]
	v_pk_mul_f32 v[50:51], v[58:59], v[50:51]
	s_waitcnt lgkmcnt(3)
	v_mov_b32_e32 v150, v169
	v_pk_mul_f32 v[60:61], v[60:61], v[150:151] op_sel_hi:[1,0]
	v_pk_mul_f32 v[62:63], v[62:63], v[150:151] op_sel_hi:[1,0]
	v_pk_mul_f32 v[56:57], v[56:57], v[150:151] op_sel_hi:[1,0]
	v_pk_mul_f32 v[58:59], v[58:59], v[150:151] op_sel_hi:[1,0]
	v_exp_f32_e32 v60, v60
	v_exp_f32_e32 v61, v61
	v_exp_f32_e32 v62, v62
	v_exp_f32_e32 v63, v63
	v_exp_f32_e32 v56, v56
	v_exp_f32_e32 v57, v57
	v_exp_f32_e32 v58, v58
	v_exp_f32_e32 v59, v59
	v_fma_f32 v60, v60, v168, v168
	v_fma_f32 v61, v61, v168, v168
	v_fma_f32 v62, v62, v168, v168
	v_fma_f32 v63, v63, v168, v168
	v_fma_f32 v56, v56, v168, v168
	v_fma_f32 v57, v57, v168, v168
	v_fma_f32 v58, v58, v168, v168
	v_fma_f32 v59, v59, v168, v168
	v_mul_f32_e32 v144, v60, v61
	v_mul_f32_e32 v146, v62, v63
	v_mul_f32_e32 v148, v56, v57
	v_mul_f32_e32 v150, v58, v59
	v_rcp_f32_e32 v144, v144
	v_rcp_f32_e32 v146, v146
	v_rcp_f32_e32 v148, v148
	v_rcp_f32_e32 v150, v150
	s_mov_b32 s8, 0xb0000
	v_pk_mul_f32 v[52:53], v[52:53], v[60:61] op_sel:[0,1] op_sel_hi:[1,0]
	v_pk_mul_f32 v[54:55], v[54:55], v[62:63] op_sel:[0,1] op_sel_hi:[1,0]
	v_pk_mul_f32 v[48:49], v[48:49], v[56:57] op_sel:[0,1] op_sel_hi:[1,0]
	v_pk_mul_f32 v[50:51], v[50:51], v[58:59] op_sel:[0,1] op_sel_hi:[1,0]
	v_pk_mul_f32 v[52:53], v[52:53], v[144:145] op_sel_hi:[1,0]
	v_pk_mul_f32 v[54:55], v[54:55], v[146:147] op_sel_hi:[1,0]
	v_pk_mul_f32 v[48:49], v[48:49], v[148:149] op_sel_hi:[1,0]
	v_pk_mul_f32 v[50:51], v[50:51], v[150:151] op_sel_hi:[1,0]
	v_cvt_pk_bf16_f32 v60, v52, v53
	v_cvt_pk_bf16_f32 v61, v54, v55
	v_cvt_pk_bf16_f32 v62, v48, v49
	v_cvt_pk_bf16_f32 v63, v50, v51
	v_lshl_add_u64 v[178:179], v[176:177], 0, s[8:9]
	global_store_dwordx4 v[178:179], v[60:63], off
	v_pk_mul_f32 v[36:37], v[44:45], v[36:37]
	v_pk_mul_f32 v[38:39], v[46:47], v[38:39]
	v_pk_mul_f32 v[32:33], v[40:41], v[32:33]
	v_pk_mul_f32 v[34:35], v[42:43], v[34:35]
	s_waitcnt lgkmcnt(2)
; __device__ __forceinline__ unsigned cvtpk(float lo, float hi) { f32x2_t v = {lo, hi}; bf16x2_t b = __builtin_convertvector(v, bf16x2_t); return __builtin_bit_cast(unsigned, b); }
; #define PG8_BAR __builtin_amdgcn_s_barrier()
; template <class Epi>
; __device__ __forceinline__ void gemm_phase(LAS unsigned char* lds, const Gemm g, const StaticOrder& S, const Epi& E, int wave_s) {
;     ...
;         if (!has_next) break;
; #pragma unroll
;         for (int a = 0; a < 2; ++a)
; #pragma unroll
;             for (int b = 0; b < 2; ++b)
; #pragma unroll
;                 for (int m = 0; m < 4; ++m)
; #pragma unroll
;                     for (int n = 0; n < 2; ++n) acc[a][b][m][n] = (f32x4){0.f, 0.f, 0.f, 0.f};
;         cur = nxt; cA = nA; cB = nB; ++ui;
;         if (wr == 1) PG8_BAR;
;     __device__ __forceinline__ void operator()(const f32x4 (&acc)[2][2][4][2], const Unit& u, int wr, int wc, int fr, int fq) const {
;     ...
;             for (int m = 0; m < 4; ++m) {
;                 const int row = row0 + ai * HALF + m * 16;
;                 const float rs = 1.0f / sqrtf(ssq_sum(ssq + (size_t)row * 16) * (1.0f / DM) + EPS);
;                 float hv[8];
; #pragma unroll
;                 for (int n = 0; n < 2; ++n)
; #pragma unroll
;                     for (int e = 0; e < 4; ++e) {
;                         const float gg = acc[ai][0][m][n][e] * rs, uu = acc[ai][1][m][n][e] * rs;
;                         const float den = 1.0f + __builtin_amdgcn_exp2f(-gg * LOG2E);
;                         hv[n * 4 + e] = gg * uu * __builtin_amdgcn_rcpf(den);
;                     }
;                 u32x4 w; w.x = cvtpk(hv[0], hv[1]); w.y = cvtpk(hv[2], hv[3]); w.z = cvtpk(hv[4], hv[5]); w.w = cvtpk(hv[6], hv[7]);
;                 *(u32x4*)(H + (size_t)row * DFF + col0) = w;
;             }
	v_mov_b32_e32 v150, v171
	v_pk_mul_f32 v[44:45], v[44:45], v[150:151] op_sel_hi:[1,0]
	v_pk_mul_f32 v[46:47], v[46:47], v[150:151] op_sel_hi:[1,0]
	v_pk_mul_f32 v[40:41], v[40:41], v[150:151] op_sel_hi:[1,0]
	v_pk_mul_f32 v[42:43], v[42:43], v[150:151] op_sel_hi:[1,0]
	v_exp_f32_e32 v44, v44
	v_exp_f32_e32 v45, v45
	v_exp_f32_e32 v46, v46
	v_exp_f32_e32 v47, v47
	v_exp_f32_e32 v40, v40
	v_exp_f32_e32 v41, v41
	v_exp_f32_e32 v42, v42
	v_exp_f32_e32 v43, v43
	v_fma_f32 v44, v44, v170, v170
	v_fma_f32 v45, v45, v170, v170
	v_fma_f32 v46, v46, v170, v170
	v_fma_f32 v47, v47, v170, v170
	v_fma_f32 v40, v40, v170, v170
	v_fma_f32 v41, v41, v170, v170
	v_fma_f32 v42, v42, v170, v170
	v_fma_f32 v43, v43, v170, v170
	v_mul_f32_e32 v144, v44, v45
	v_mul_f32_e32 v146, v46, v47
	v_mul_f32_e32 v148, v40, v41
	v_mul_f32_e32 v150, v42, v43
	v_rcp_f32_e32 v144, v144
	v_rcp_f32_e32 v146, v146
	v_rcp_f32_e32 v148, v148
	v_rcp_f32_e32 v150, v150
	s_mov_b32 s8, 0xc6000
	v_pk_mul_f32 v[36:37], v[36:37], v[44:45] op_sel:[0,1] op_sel_hi:[1,0]
	v_pk_mul_f32 v[38:39], v[38:39], v[46:47] op_sel:[0,1] op_sel_hi:[1,0]
	v_pk_mul_f32 v[32:33], v[32:33], v[40:41] op_sel:[0,1] op_sel_hi:[1,0]
	v_pk_mul_f32 v[34:35], v[34:35], v[42:43] op_sel:[0,1] op_sel_hi:[1,0]
	v_pk_mul_f32 v[36:37], v[36:37], v[144:145] op_sel_hi:[1,0]
	v_pk_mul_f32 v[38:39], v[38:39], v[146:147] op_sel_hi:[1,0]
	v_pk_mul_f32 v[32:33], v[32:33], v[148:149] op_sel_hi:[1,0]
	v_pk_mul_f32 v[34:35], v[34:35], v[150:151] op_sel_hi:[1,0]
	v_cvt_pk_bf16_f32 v44, v36, v37
	v_cvt_pk_bf16_f32 v45, v38, v39
	v_cvt_pk_bf16_f32 v46, v32, v33
	v_cvt_pk_bf16_f32 v47, v34, v35
	v_lshl_add_u64 v[178:179], v[176:177], 0, s[8:9]
	global_store_dwordx4 v[178:179], v[44:47], off
	v_pk_mul_f32 v[20:21], v[28:29], v[20:21]
	v_pk_mul_f32 v[22:23], v[30:31], v[22:23]
	v_pk_mul_f32 v[16:17], v[24:25], v[16:17]
	v_pk_mul_f32 v[18:19], v[26:27], v[18:19]
	s_waitcnt lgkmcnt(1)
	v_mov_b32_e32 v150, v173
	v_pk_mul_f32 v[28:29], v[28:29], v[150:151] op_sel_hi:[1,0]
	v_pk_mul_f32 v[30:31], v[30:31], v[150:151] op_sel_hi:[1,0]
	v_pk_mul_f32 v[24:25], v[24:25], v[150:151] op_sel_hi:[1,0]
	v_pk_mul_f32 v[26:27], v[26:27], v[150:151] op_sel_hi:[1,0]
	v_exp_f32_e32 v28, v28
	v_exp_f32_e32 v29, v29
	v_exp_f32_e32 v30, v30
	v_exp_f32_e32 v31, v31
	v_exp_f32_e32 v24, v24
	v_exp_f32_e32 v25, v25
	v_exp_f32_e32 v26, v26
	v_exp_f32_e32 v27, v27
	v_fma_f32 v28, v28, v172, v172
	v_fma_f32 v29, v29, v172, v172
	v_fma_f32 v30, v30, v172, v172
	v_fma_f32 v31, v31, v172, v172
	v_fma_f32 v24, v24, v172, v172
	v_fma_f32 v25, v25, v172, v172
	v_fma_f32 v26, v26, v172, v172
	v_fma_f32 v27, v27, v172, v172
	v_mul_f32_e32 v144, v28, v29
	v_mul_f32_e32 v146, v30, v31
	v_mul_f32_e32 v148, v24, v25
	v_mul_f32_e32 v150, v26, v27
	v_rcp_f32_e32 v144, v144
	v_rcp_f32_e32 v146, v146
	v_rcp_f32_e32 v148, v148
	v_rcp_f32_e32 v150, v150
	s_mov_b32 s8, 0xdc000
	v_pk_mul_f32 v[20:21], v[20:21], v[28:29] op_sel:[0,1] op_sel_hi:[1,0]
	v_pk_mul_f32 v[22:23], v[22:23], v[30:31] op_sel:[0,1] op_sel_hi:[1,0]
	v_pk_mul_f32 v[16:17], v[16:17], v[24:25] op_sel:[0,1] op_sel_hi:[1,0]
	v_pk_mul_f32 v[18:19], v[18:19], v[26:27] op_sel:[0,1] op_sel_hi:[1,0]
	v_pk_mul_f32 v[20:21], v[20:21], v[144:145] op_sel_hi:[1,0]
	v_pk_mul_f32 v[22:23], v[22:23], v[146:147] op_sel_hi:[1,0]
	v_pk_mul_f32 v[16:17], v[16:17], v[148:149] op_sel_hi:[1,0]
	v_pk_mul_f32 v[18:19], v[18:19], v[150:151] op_sel_hi:[1,0]
	v_cvt_pk_bf16_f32 v28, v20, v21
	v_cvt_pk_bf16_f32 v29, v22, v23
	v_cvt_pk_bf16_f32 v30, v16, v17
	v_cvt_pk_bf16_f32 v31, v18, v19
	v_lshl_add_u64 v[178:179], v[176:177], 0, s[8:9]
	global_store_dwordx4 v[178:179], v[28:31], off
	v_pk_mul_f32 v[4:5], v[12:13], v[4:5]
	v_pk_mul_f32 v[6:7], v[14:15], v[6:7]
	v_pk_mul_f32 v[0:1], v[8:9], v[0:1]
	v_pk_mul_f32 v[2:3], v[10:11], v[2:3]
	s_waitcnt lgkmcnt(0)
	v_mov_b32_e32 v150, v175
	v_pk_mul_f32 v[12:13], v[12:13], v[150:151] op_sel_hi:[1,0]
	v_pk_mul_f32 v[14:15], v[14:15], v[150:151] op_sel_hi:[1,0]
	v_pk_mul_f32 v[8:9], v[8:9], v[150:151] op_sel_hi:[1,0]
	v_pk_mul_f32 v[10:11], v[10:11], v[150:151] op_sel_hi:[1,0]
	v_exp_f32_e32 v12, v12
	v_exp_f32_e32 v13, v13
	v_exp_f32_e32 v14, v14
	v_exp_f32_e32 v15, v15
	v_exp_f32_e32 v8, v8
	v_exp_f32_e32 v9, v9
	v_exp_f32_e32 v10, v10
	v_exp_f32_e32 v11, v11
	v_fma_f32 v12, v12, v174, v174
	v_fma_f32 v13, v13, v174, v174
	v_fma_f32 v14, v14, v174, v174
	v_fma_f32 v15, v15, v174, v174
	v_fma_f32 v8, v8, v174, v174
	v_fma_f32 v9, v9, v174, v174
	v_fma_f32 v10, v10, v174, v174
	v_fma_f32 v11, v11, v174, v174
	v_mul_f32_e32 v144, v12, v13
	v_mul_f32_e32 v146, v14, v15
	v_mul_f32_e32 v148, v8, v9
	v_mul_f32_e32 v150, v10, v11
	v_rcp_f32_e32 v144, v144
	v_rcp_f32_e32 v146, v146
	v_rcp_f32_e32 v148, v148
	v_rcp_f32_e32 v150, v150
	s_mov_b32 s8, 0xf2000
	v_pk_mul_f32 v[4:5], v[4:5], v[12:13] op_sel:[0,1] op_sel_hi:[1,0]
	v_pk_mul_f32 v[6:7], v[6:7], v[14:15] op_sel:[0,1] op_sel_hi:[1,0]
	v_pk_mul_f32 v[0:1], v[0:1], v[8:9] op_sel:[0,1] op_sel_hi:[1,0]
	v_pk_mul_f32 v[2:3], v[2:3], v[10:11] op_sel:[0,1] op_sel_hi:[1,0]
	v_pk_mul_f32 v[4:5], v[4:5], v[144:145] op_sel_hi:[1,0]
	v_pk_mul_f32 v[6:7], v[6:7], v[146:147] op_sel_hi:[1,0]
	v_pk_mul_f32 v[0:1], v[0:1], v[148:149] op_sel_hi:[1,0]
	v_pk_mul_f32 v[2:3], v[2:3], v[150:151] op_sel_hi:[1,0]
	v_cvt_pk_bf16_f32 v12, v4, v5
	v_cvt_pk_bf16_f32 v13, v6, v7
	v_cvt_pk_bf16_f32 v14, v0, v1
	v_cvt_pk_bf16_f32 v15, v2, v3
	v_lshl_add_u64 v[178:179], v[176:177], 0, s[8:9]
	global_store_dwordx4 v[178:179], v[12:15], off
	s_andn2_b64 vcc, exec, s[6:7]
	s_mov_b64 s[6:7], -1
	s_cbranch_vccnz .LBB0_237
	s_andn2_b64 vcc, exec, s[12:13]
	s_cbranch_vccnz .LBB0_236
	s_barrier
	s_branch .LBB0_236

; __device__ __forceinline__ unsigned cvtpk(float lo, float hi) { f32x2_t v = {lo, hi}; bf16x2_t b = __builtin_convertvector(v, bf16x2_t); return __builtin_bit_cast(unsigned, b); }
;     __device__ __forceinline__ void operator()(const f32x4 (&acc)[2][2][4][2], const Unit& u, int wr, int wc, int fr, int fq) const {
;         const int row0 = u.pm * BM + wr * 64 + fr, col0 = u.pn * 128 + wc * 32 + 8 * fq;
; #pragma unroll
;         for (int ai = 0; ai < 2; ++ai)
; #pragma unroll
;             for (int m = 0; m < 4; ++m) {
;                 const int row = row0 + ai * HALF + m * 16;
;                 const float rs = 1.0f / sqrtf(ssq_sum(ssq + (size_t)row * 16) * (1.0f / DM) + EPS);
;                 float hv[8];
; #pragma unroll
;                 for (int n = 0; n < 2; ++n)
; #pragma unroll
;                     for (int e = 0; e < 4; ++e) {
;                         const float gg = acc[ai][0][m][n][e] * rs, uu = acc[ai][1][m][n][e] * rs;
;                         const float den = 1.0f + __builtin_amdgcn_exp2f(-gg * LOG2E);
;                         hv[n * 4 + e] = gg * uu * __builtin_amdgcn_rcpf(den);
;                     }
;                 u32x4 w; w.x = cvtpk(hv[0], hv[1]); w.y = cvtpk(hv[2], hv[3]); w.z = cvtpk(hv[4], hv[5]); w.w = cvtpk(hv[6], hv[7]);
;                 *(u32x4*)(H + (size_t)row * DFF + col0) = w;
.LBB0_1054:
	v_readlane_b32 s9, v254, 7
	v_mbcnt_lo_u32_b32 v144, -1, 0
	v_mbcnt_hi_u32_b32 v144, -1, v144
	v_lshrrev_b32_e32 v145, 1, v144
	v_lshl_add_u32 v145, s9, 5, v145
	v_and_b32_e32 v146, 1, v144
	v_lshl_add_u32 v147, s8, 8, v145
	v_lshlrev_b32_e32 v147, 6, v147
	v_lshl_add_u32 v147, v146, 5, v147
	global_load_dwordx4 v[160:163], v147, s[16:17]
	global_load_dwordx4 v[164:167], v147, s[16:17] offset:16
	v_lshl_add_u32 v148, s8, 8, v152
	v_mov_b64_e32 v[146:147], s[14:15]
	v_mad_i64_i32 v[176:177], s[8:9], v148, s51, v[146:147]
	v_lshl_or_b32 v150, s2, 7, v154
	v_mov_b32_e32 v151, 0
	v_lshlrev_b64 v[150:151], 1, v[150:151]
	v_lshl_add_u64 v[176:177], v[176:177], 0, v[150:151]
	v_lshlrev_b32_e32 v145, 3, v145
	v_add_u32_e32 v145, 0x20100, v145
	v_lshlrev_b32_e32 v146, 3, v152
	v_add_u32_e32 v146, 0x20100, v146
	s_mov_b32 s9, 0
	s_waitcnt vmcnt(0)
	v_pk_add_f32 v[160:161], v[160:161], v[162:163]
	v_pk_add_f32 v[164:165], v[164:165], v[166:167]
	v_pk_add_f32 v[160:161], v[160:161], v[164:165]
	v_add_f32_e32 v160, v160, v161
	s_nop 1
	v_add_f32_dpp v160, v160, v160 quad_perm:[1,0,3,2] row_mask:0xf bank_mask:0xf
	v_fmamk_f32 v160, v160, 0x3a800000, v158
	v_rsq_f32_e32 v161, v160
	s_nop 0
	v_mul_f32_e32 v161, 0xbfb8aa3b, v161
	ds_write_b64 v145, v[160:161]
	s_waitcnt lgkmcnt(0)
	s_barrier
	ds_read_b64 v[160:161], v146 offset:0
	ds_read_b64 v[162:163], v146 offset:128
	ds_read_b64 v[164:165], v146 offset:256
	ds_read_b64 v[166:167], v146 offset:384
	ds_read_b64 v[168:169], v146 offset:1024
	ds_read_b64 v[170:171], v146 offset:1152
	ds_read_b64 v[172:173], v146 offset:1280
	ds_read_b64 v[174:175], v146 offset:1408
	v_pk_mul_f32 v[116:117], v[124:125], v[116:117]
	v_pk_mul_f32 v[118:119], v[126:127], v[118:119]
	v_pk_mul_f32 v[112:113], v[120:121], v[112:113]
	v_pk_mul_f32 v[114:115], v[122:123], v[114:115]
	s_waitcnt lgkmcnt(7)
	v_mov_b32_e32 v150, v161
	v_pk_mul_f32 v[124:125], v[124:125], v[150:151] op_sel_hi:[1,0]
	v_pk_mul_f32 v[126:127], v[126:127], v[150:151] op_sel_hi:[1,0]
	v_pk_mul_f32 v[120:121], v[120:121], v[150:151] op_sel_hi:[1,0]
	v_pk_mul_f32 v[122:123], v[122:123], v[150:151] op_sel_hi:[1,0]
	v_exp_f32_e32 v124, v124
	v_exp_f32_e32 v125, v125
	v_exp_f32_e32 v126, v126
	v_exp_f32_e32 v127, v127
	v_exp_f32_e32 v120, v120
	v_exp_f32_e32 v121, v121
	v_exp_f32_e32 v122, v122
	v_exp_f32_e32 v123, v123
	v_fma_f32 v124, v124, v160, v160
	v_fma_f32 v125, v125, v160, v160
	v_fma_f32 v126, v126, v160, v160
	v_fma_f32 v127, v127, v160, v160
	v_fma_f32 v120, v120, v160, v160
	v_fma_f32 v121, v121, v160, v160
	v_fma_f32 v122, v122, v160, v160
	v_fma_f32 v123, v123, v160, v160
	v_mul_f32_e32 v144, v124, v125
	v_mul_f32_e32 v146, v126, v127
	v_mul_f32_e32 v148, v120, v121
	v_mul_f32_e32 v150, v122, v123
	v_rcp_f32_e32 v144, v144
	v_rcp_f32_e32 v146, v146
	v_rcp_f32_e32 v148, v148
	v_rcp_f32_e32 v150, v150
	v_pk_mul_f32 v[116:117], v[116:117], v[124:125] op_sel:[0,1] op_sel_hi:[1,0]
	v_pk_mul_f32 v[118:119], v[118:119], v[126:127] op_sel:[0,1] op_sel_hi:[1,0]
	v_pk_mul_f32 v[112:113], v[112:113], v[120:121] op_sel:[0,1] op_sel_hi:[1,0]
	v_pk_mul_f32 v[114:115], v[114:115], v[122:123] op_sel:[0,1] op_sel_hi:[1,0]
	v_pk_mul_f32 v[116:117], v[116:117], v[144:145] op_sel_hi:[1,0]
	v_pk_mul_f32 v[118:119], v[118:119], v[146:147] op_sel_hi:[1,0]
	v_pk_mul_f32 v[112:113], v[112:113], v[148:149] op_sel_hi:[1,0]
	v_pk_mul_f32 v[114:115], v[114:115], v[150:151] op_sel_hi:[1,0]
	v_cvt_pk_bf16_f32 v124, v116, v117
	v_cvt_pk_bf16_f32 v125, v118, v119
	v_cvt_pk_bf16_f32 v126, v112, v113
	v_cvt_pk_bf16_f32 v127, v114, v115
	global_store_dwordx4 v[176:177], v[124:127], off
	v_pk_mul_f32 v[100:101], v[108:109], v[100:101]
	v_pk_mul_f32 v[102:103], v[110:111], v[102:103]
	v_pk_mul_f32 v[96:97], v[104:105], v[96:97]
	v_pk_mul_f32 v[98:99], v[106:107], v[98:99]
	s_waitcnt lgkmcnt(6)
	v_mov_b32_e32 v150, v163
	v_pk_mul_f32 v[108:109], v[108:109], v[150:151] op_sel_hi:[1,0]
	v_pk_mul_f32 v[110:111], v[110:111], v[150:151] op_sel_hi:[1,0]
	v_pk_mul_f32 v[104:105], v[104:105], v[150:151] op_sel_hi:[1,0]
	v_pk_mul_f32 v[106:107], v[106:107], v[150:151] op_sel_hi:[1,0]
	v_exp_f32_e32 v108, v108
	v_exp_f32_e32 v109, v109
	v_exp_f32_e32 v110, v110
	v_exp_f32_e32 v111, v111
	v_exp_f32_e32 v104, v104
	v_exp_f32_e32 v105, v105
	v_exp_f32_e32 v106, v106
	v_exp_f32_e32 v107, v107
	v_fma_f32 v108, v108, v162, v162
	v_fma_f32 v109, v109, v162, v162
	v_fma_f32 v110, v110, v162, v162
	v_fma_f32 v111, v111, v162, v162
	v_fma_f32 v104, v104, v162, v162
	v_fma_f32 v105, v105, v162, v162
	v_fma_f32 v106, v106, v162, v162
	v_fma_f32 v107, v107, v162, v162
	v_mul_f32_e32 v144, v108, v109
	v_mul_f32_e32 v146, v110, v111
	v_mul_f32_e32 v148, v104, v105
	v_mul_f32_e32 v150, v106, v107
	v_rcp_f32_e32 v144, v144
	v_rcp_f32_e32 v146, v146
	v_rcp_f32_e32 v148, v148
	v_rcp_f32_e32 v150, v150
	s_mov_b32 s8, 0x16000
	v_pk_mul_f32 v[100:101], v[100:101], v[108:109] op_sel:[0,1] op_sel_hi:[1,0]
	v_pk_mul_f32 v[102:103], v[102:103], v[110:111] op_sel:[0,1] op_sel_hi:[1,0]
	v_pk_mul_f32 v[96:97], v[96:97], v[104:105] op_sel:[0,1] op_sel_hi:[1,0]
	v_pk_mul_f32 v[98:99], v[98:99], v[106:107] op_sel:[0,1] op_sel_hi:[1,0]
	v_pk_mul_f32 v[100:101], v[100:101], v[144:145] op_sel_hi:[1,0]
	v_pk_mul_f32 v[102:103], v[102:103], v[146:147] op_sel_hi:[1,0]
	v_pk_mul_f32 v[96:97], v[96:97], v[148:149] op_sel_hi:[1,0]
	v_pk_mul_f32 v[98:99], v[98:99], v[150:151] op_sel_hi:[1,0]
	v_cvt_pk_bf16_f32 v108, v100, v101
	v_cvt_pk_bf16_f32 v109, v102, v103
	v_cvt_pk_bf16_f32 v110, v96, v97
	v_cvt_pk_bf16_f32 v111, v98, v99
	v_lshl_add_u64 v[178:179], v[176:177], 0, s[8:9]
	global_store_dwordx4 v[178:179], v[108:111], off
	v_pk_mul_f32 v[84:85], v[92:93], v[84:85]
	v_pk_mul_f32 v[86:87], v[94:95], v[86:87]
	v_pk_mul_f32 v[80:81], v[88:89], v[80:81]
	v_pk_mul_f32 v[82:83], v[90:91], v[82:83]
	s_waitcnt lgkmcnt(5)
; __device__ __forceinline__ unsigned cvtpk(float lo, float hi) { f32x2_t v = {lo, hi}; bf16x2_t b = __builtin_convertvector(v, bf16x2_t); return __builtin_bit_cast(unsigned, b); }
;     __device__ __forceinline__ void operator()(const f32x4 (&acc)[2][2][4][2], const Unit& u, int wr, int wc, int fr, int fq) const {
;     ...
;             for (int m = 0; m < 4; ++m) {
;                 const int row = row0 + ai * HALF + m * 16;
;                 const float rs = 1.0f / sqrtf(ssq_sum(ssq + (size_t)row * 16) * (1.0f / DM) + EPS);
;                 float hv[8];
; #pragma unroll
;                 for (int n = 0; n < 2; ++n)
; #pragma unroll
;                     for (int e = 0; e < 4; ++e) {
;                         const float gg = acc[ai][0][m][n][e] * rs, uu = acc[ai][1][m][n][e] * rs;
;                         const float den = 1.0f + __builtin_amdgcn_exp2f(-gg * LOG2E);
;                         hv[n * 4 + e] = gg * uu * __builtin_amdgcn_rcpf(den);
;                     }
;                 u32x4 w; w.x = cvtpk(hv[0], hv[1]); w.y = cvtpk(hv[2], hv[3]); w.z = cvtpk(hv[4], hv[5]); w.w = cvtpk(hv[6], hv[7]);
;                 *(u32x4*)(H + (size_t)row * DFF + col0) = w;
	v_mov_b32_e32 v150, v165
	v_pk_mul_f32 v[92:93], v[92:93], v[150:151] op_sel_hi:[1,0]
	v_pk_mul_f32 v[94:95], v[94:95], v[150:151] op_sel_hi:[1,0]
	v_pk_mul_f32 v[88:89], v[88:89], v[150:151] op_sel_hi:[1,0]
	v_pk_mul_f32 v[90:91], v[90:91], v[150:151] op_sel_hi:[1,0]
	v_exp_f32_e32 v92, v92
	v_exp_f32_e32 v93, v93
	v_exp_f32_e32 v94, v94
	v_exp_f32_e32 v95, v95
	v_exp_f32_e32 v88, v88
	v_exp_f32_e32 v89, v89
	v_exp_f32_e32 v90, v90
	v_exp_f32_e32 v91, v91
	v_fma_f32 v92, v92, v164, v164
	v_fma_f32 v93, v93, v164, v164
	v_fma_f32 v94, v94, v164, v164
	v_fma_f32 v95, v95, v164, v164
	v_fma_f32 v88, v88, v164, v164
	v_fma_f32 v89, v89, v164, v164
	v_fma_f32 v90, v90, v164, v164
	v_fma_f32 v91, v91, v164, v164
	v_mul_f32_e32 v144, v92, v93
	v_mul_f32_e32 v146, v94, v95
	v_mul_f32_e32 v148, v88, v89
	v_mul_f32_e32 v150, v90, v91
	v_rcp_f32_e32 v144, v144
	v_rcp_f32_e32 v146, v146
	v_rcp_f32_e32 v148, v148
	v_rcp_f32_e32 v150, v150
	s_mov_b32 s8, 0x2c000
	v_pk_mul_f32 v[84:85], v[84:85], v[92:93] op_sel:[0,1] op_sel_hi:[1,0]
	v_pk_mul_f32 v[86:87], v[86:87], v[94:95] op_sel:[0,1] op_sel_hi:[1,0]
	v_pk_mul_f32 v[80:81], v[80:81], v[88:89] op_sel:[0,1] op_sel_hi:[1,0]
	v_pk_mul_f32 v[82:83], v[82:83], v[90:91] op_sel:[0,1] op_sel_hi:[1,0]
	v_pk_mul_f32 v[84:85], v[84:85], v[144:145] op_sel_hi:[1,0]
	v_pk_mul_f32 v[86:87], v[86:87], v[146:147] op_sel_hi:[1,0]
	v_pk_mul_f32 v[80:81], v[80:81], v[148:149] op_sel_hi:[1,0]
	v_pk_mul_f32 v[82:83], v[82:83], v[150:151] op_sel_hi:[1,0]
	v_cvt_pk_bf16_f32 v92, v84, v85
	v_cvt_pk_bf16_f32 v93, v86, v87
	v_cvt_pk_bf16_f32 v94, v80, v81
	v_cvt_pk_bf16_f32 v95, v82, v83
	v_lshl_add_u64 v[178:179], v[176:177], 0, s[8:9]
	global_store_dwordx4 v[178:179], v[92:95], off
	v_pk_mul_f32 v[68:69], v[76:77], v[68:69]
	v_pk_mul_f32 v[70:71], v[78:79], v[70:71]
	v_pk_mul_f32 v[64:65], v[72:73], v[64:65]
	v_pk_mul_f32 v[66:67], v[74:75], v[66:67]
	s_waitcnt lgkmcnt(4)
	v_mov_b32_e32 v150, v167
	v_pk_mul_f32 v[76:77], v[76:77], v[150:151] op_sel_hi:[1,0]
	v_pk_mul_f32 v[78:79], v[78:79], v[150:151] op_sel_hi:[1,0]
	v_pk_mul_f32 v[72:73], v[72:73], v[150:151] op_sel_hi:[1,0]
	v_pk_mul_f32 v[74:75], v[74:75], v[150:151] op_sel_hi:[1,0]
	v_exp_f32_e32 v76, v76
	v_exp_f32_e32 v77, v77
	v_exp_f32_e32 v78, v78
	v_exp_f32_e32 v79, v79
	v_exp_f32_e32 v72, v72
	v_exp_f32_e32 v73, v73
	v_exp_f32_e32 v74, v74
	v_exp_f32_e32 v75, v75
	v_fma_f32 v76, v76, v166, v166
	v_fma_f32 v77, v77, v166, v166
	v_fma_f32 v78, v78, v166, v166
	v_fma_f32 v79, v79, v166, v166
	v_fma_f32 v72, v72, v166, v166
	v_fma_f32 v73, v73, v166, v166
	v_fma_f32 v74, v74, v166, v166
	v_fma_f32 v75, v75, v166, v166
	v_mul_f32_e32 v144, v76, v77
	v_mul_f32_e32 v146, v78, v79
	v_mul_f32_e32 v148, v72, v73
	v_mul_f32_e32 v150, v74, v75
	v_rcp_f32_e32 v144, v144
	v_rcp_f32_e32 v146, v146
	v_rcp_f32_e32 v148, v148
	v_rcp_f32_e32 v150, v150
	s_mov_b32 s8, 0x42000
	v_pk_mul_f32 v[68:69], v[68:69], v[76:77] op_sel:[0,1] op_sel_hi:[1,0]
	v_pk_mul_f32 v[70:71], v[70:71], v[78:79] op_sel:[0,1] op_sel_hi:[1,0]
	v_pk_mul_f32 v[64:65], v[64:65], v[72:73] op_sel:[0,1] op_sel_hi:[1,0]
	v_pk_mul_f32 v[66:67], v[66:67], v[74:75] op_sel:[0,1] op_sel_hi:[1,0]
	v_pk_mul_f32 v[68:69], v[68:69], v[144:145] op_sel_hi:[1,0]
	v_pk_mul_f32 v[70:71], v[70:71], v[146:147] op_sel_hi:[1,0]
	v_pk_mul_f32 v[64:65], v[64:65], v[148:149] op_sel_hi:[1,0]
	v_pk_mul_f32 v[66:67], v[66:67], v[150:151] op_sel_hi:[1,0]
	v_cvt_pk_bf16_f32 v76, v68, v69
	v_cvt_pk_bf16_f32 v77, v70, v71
	v_cvt_pk_bf16_f32 v78, v64, v65
	v_cvt_pk_bf16_f32 v79, v66, v67
	v_lshl_add_u64 v[178:179], v[176:177], 0, s[8:9]
	global_store_dwordx4 v[178:179], v[76:79], off
	v_pk_mul_f32 v[52:53], v[60:61], v[52:53]
	v_pk_mul_f32 v[54:55], v[62:63], v[54:55]
	v_pk_mul_f32 v[48:49], v[56:57], v[48:49]
	v_pk_mul_f32 v[50:51], v[58:59], v[50:51]
	s_waitcnt lgkmcnt(3)
	v_mov_b32_e32 v150, v169
	v_pk_mul_f32 v[60:61], v[60:61], v[150:151] op_sel_hi:[1,0]
	v_pk_mul_f32 v[62:63], v[62:63], v[150:151] op_sel_hi:[1,0]
	v_pk_mul_f32 v[56:57], v[56:57], v[150:151] op_sel_hi:[1,0]
	v_pk_mul_f32 v[58:59], v[58:59], v[150:151] op_sel_hi:[1,0]
	v_exp_f32_e32 v60, v60
	v_exp_f32_e32 v61, v61
	v_exp_f32_e32 v62, v62
	v_exp_f32_e32 v63, v63
	v_exp_f32_e32 v56, v56
	v_exp_f32_e32 v57, v57
	v_exp_f32_e32 v58, v58
	v_exp_f32_e32 v59, v59
	v_fma_f32 v60, v60, v168, v168
	v_fma_f32 v61, v61, v168, v168
	v_fma_f32 v62, v62, v168, v168
	v_fma_f32 v63, v63, v168, v168
	v_fma_f32 v56, v56, v168, v168
	v_fma_f32 v57, v57, v168, v168
	v_fma_f32 v58, v58, v168, v168
	v_fma_f32 v59, v59, v168, v168
	v_mul_f32_e32 v144, v60, v61
	v_mul_f32_e32 v146, v62, v63
	v_mul_f32_e32 v148, v56, v57
	v_mul_f32_e32 v150, v58, v59
	v_rcp_f32_e32 v144, v144
	v_rcp_f32_e32 v146, v146
	v_rcp_f32_e32 v148, v148
	v_rcp_f32_e32 v150, v150
	s_mov_b32 s8, 0xb0000
	v_pk_mul_f32 v[52:53], v[52:53], v[60:61] op_sel:[0,1] op_sel_hi:[1,0]
	v_pk_mul_f32 v[54:55], v[54:55], v[62:63] op_sel:[0,1] op_sel_hi:[1,0]
	v_pk_mul_f32 v[48:49], v[48:49], v[56:57] op_sel:[0,1] op_sel_hi:[1,0]
	v_pk_mul_f32 v[50:51], v[50:51], v[58:59] op_sel:[0,1] op_sel_hi:[1,0]
	v_pk_mul_f32 v[52:53], v[52:53], v[144:145] op_sel_hi:[1,0]
	v_pk_mul_f32 v[54:55], v[54:55], v[146:147] op_sel_hi:[1,0]
	v_pk_mul_f32 v[48:49], v[48:49], v[148:149] op_sel_hi:[1,0]
	v_pk_mul_f32 v[50:51], v[50:51], v[150:151] op_sel_hi:[1,0]
	v_cvt_pk_bf16_f32 v60, v52, v53
	v_cvt_pk_bf16_f32 v61, v54, v55
	v_cvt_pk_bf16_f32 v62, v48, v49
	v_cvt_pk_bf16_f32 v63, v50, v51
	v_lshl_add_u64 v[178:179], v[176:177], 0, s[8:9]
	global_store_dwordx4 v[178:179], v[60:63], off
	v_pk_mul_f32 v[36:37], v[44:45], v[36:37]
	v_pk_mul_f32 v[38:39], v[46:47], v[38:39]
	v_pk_mul_f32 v[32:33], v[40:41], v[32:33]
	v_pk_mul_f32 v[34:35], v[42:43], v[34:35]
	s_waitcnt lgkmcnt(2)
; __device__ __forceinline__ unsigned cvtpk(float lo, float hi) { f32x2_t v = {lo, hi}; bf16x2_t b = __builtin_convertvector(v, bf16x2_t); return __builtin_bit_cast(unsigned, b); }
; #define PG8_BAR __builtin_amdgcn_s_barrier()
; template <class Epi>
; __device__ __forceinline__ void gemm_phase(LAS unsigned char* lds, const Gemm g, const StaticOrder& S, const Epi& E, int wave_s) {
;     ...
;         if (!has_next) break;
; #pragma unroll
;         for (int a = 0; a < 2; ++a)
; #pragma unroll
;             for (int b = 0; b < 2; ++b)
; #pragma unroll
;                 for (int m = 0; m < 4; ++m)
; #pragma unroll
;                     for (int n = 0; n < 2; ++n) acc[a][b][m][n] = (f32x4){0.f, 0.f, 0.f, 0.f};
;         cur = nxt; cA = nA; cB = nB; ++ui;
;         if (wr == 1) PG8_BAR;
;     __device__ __forceinline__ void operator()(const f32x4 (&acc)[2][2][4][2], const Unit& u, int wr, int wc, int fr, int fq) const {
;     ...
;             for (int m = 0; m < 4; ++m) {
;                 const int row = row0 + ai * HALF + m * 16;
;                 const float rs = 1.0f / sqrtf(ssq_sum(ssq + (size_t)row * 16) * (1.0f / DM) + EPS);
;                 float hv[8];
; #pragma unroll
;                 for (int n = 0; n < 2; ++n)
; #pragma unroll
;                     for (int e = 0; e < 4; ++e) {
;                         const float gg = acc[ai][0][m][n][e] * rs, uu = acc[ai][1][m][n][e] * rs;
;                         const float den = 1.0f + __builtin_amdgcn_exp2f(-gg * LOG2E);
;                         hv[n * 4 + e] = gg * uu * __builtin_amdgcn_rcpf(den);
;                     }
;                 u32x4 w; w.x = cvtpk(hv[0], hv[1]); w.y = cvtpk(hv[2], hv[3]); w.z = cvtpk(hv[4], hv[5]); w.w = cvtpk(hv[6], hv[7]);
;                 *(u32x4*)(H + (size_t)row * DFF + col0) = w;
;             }
	v_mov_b32_e32 v150, v171
	v_pk_mul_f32 v[44:45], v[44:45], v[150:151] op_sel_hi:[1,0]
	v_pk_mul_f32 v[46:47], v[46:47], v[150:151] op_sel_hi:[1,0]
	v_pk_mul_f32 v[40:41], v[40:41], v[150:151] op_sel_hi:[1,0]
	v_pk_mul_f32 v[42:43], v[42:43], v[150:151] op_sel_hi:[1,0]
	v_exp_f32_e32 v44, v44
	v_exp_f32_e32 v45, v45
	v_exp_f32_e32 v46, v46
	v_exp_f32_e32 v47, v47
	v_exp_f32_e32 v40, v40
	v_exp_f32_e32 v41, v41
	v_exp_f32_e32 v42, v42
	v_exp_f32_e32 v43, v43
	v_fma_f32 v44, v44, v170, v170
	v_fma_f32 v45, v45, v170, v170
	v_fma_f32 v46, v46, v170, v170
	v_fma_f32 v47, v47, v170, v170
	v_fma_f32 v40, v40, v170, v170
	v_fma_f32 v41, v41, v170, v170
	v_fma_f32 v42, v42, v170, v170
	v_fma_f32 v43, v43, v170, v170
	v_mul_f32_e32 v144, v44, v45
	v_mul_f32_e32 v146, v46, v47
	v_mul_f32_e32 v148, v40, v41
	v_mul_f32_e32 v150, v42, v43
	v_rcp_f32_e32 v144, v144
	v_rcp_f32_e32 v146, v146
	v_rcp_f32_e32 v148, v148
	v_rcp_f32_e32 v150, v150
	s_mov_b32 s8, 0xc6000
	v_pk_mul_f32 v[36:37], v[36:37], v[44:45] op_sel:[0,1] op_sel_hi:[1,0]
	v_pk_mul_f32 v[38:39], v[38:39], v[46:47] op_sel:[0,1] op_sel_hi:[1,0]
	v_pk_mul_f32 v[32:33], v[32:33], v[40:41] op_sel:[0,1] op_sel_hi:[1,0]
	v_pk_mul_f32 v[34:35], v[34:35], v[42:43] op_sel:[0,1] op_sel_hi:[1,0]
	v_pk_mul_f32 v[36:37], v[36:37], v[144:145] op_sel_hi:[1,0]
	v_pk_mul_f32 v[38:39], v[38:39], v[146:147] op_sel_hi:[1,0]
	v_pk_mul_f32 v[32:33], v[32:33], v[148:149] op_sel_hi:[1,0]
	v_pk_mul_f32 v[34:35], v[34:35], v[150:151] op_sel_hi:[1,0]
	v_cvt_pk_bf16_f32 v44, v36, v37
	v_cvt_pk_bf16_f32 v45, v38, v39
	v_cvt_pk_bf16_f32 v46, v32, v33
	v_cvt_pk_bf16_f32 v47, v34, v35
	v_lshl_add_u64 v[178:179], v[176:177], 0, s[8:9]
	global_store_dwordx4 v[178:179], v[44:47], off
	v_pk_mul_f32 v[20:21], v[28:29], v[20:21]
	v_pk_mul_f32 v[22:23], v[30:31], v[22:23]
	v_pk_mul_f32 v[16:17], v[24:25], v[16:17]
	v_pk_mul_f32 v[18:19], v[26:27], v[18:19]
	s_waitcnt lgkmcnt(1)
	v_mov_b32_e32 v150, v173
	v_pk_mul_f32 v[28:29], v[28:29], v[150:151] op_sel_hi:[1,0]
	v_pk_mul_f32 v[30:31], v[30:31], v[150:151] op_sel_hi:[1,0]
	v_pk_mul_f32 v[24:25], v[24:25], v[150:151] op_sel_hi:[1,0]
	v_pk_mul_f32 v[26:27], v[26:27], v[150:151] op_sel_hi:[1,0]
	v_exp_f32_e32 v28, v28
	v_exp_f32_e32 v29, v29
	v_exp_f32_e32 v30, v30
	v_exp_f32_e32 v31, v31
	v_exp_f32_e32 v24, v24
	v_exp_f32_e32 v25, v25
	v_exp_f32_e32 v26, v26
	v_exp_f32_e32 v27, v27
	v_fma_f32 v28, v28, v172, v172
	v_fma_f32 v29, v29, v172, v172
	v_fma_f32 v30, v30, v172, v172
	v_fma_f32 v31, v31, v172, v172
	v_fma_f32 v24, v24, v172, v172
	v_fma_f32 v25, v25, v172, v172
	v_fma_f32 v26, v26, v172, v172
	v_fma_f32 v27, v27, v172, v172
	v_mul_f32_e32 v144, v28, v29
	v_mul_f32_e32 v146, v30, v31
	v_mul_f32_e32 v148, v24, v25
	v_mul_f32_e32 v150, v26, v27
	v_rcp_f32_e32 v144, v144
	v_rcp_f32_e32 v146, v146
	v_rcp_f32_e32 v148, v148
	v_rcp_f32_e32 v150, v150
	s_mov_b32 s8, 0xdc000
	v_pk_mul_f32 v[20:21], v[20:21], v[28:29] op_sel:[0,1] op_sel_hi:[1,0]
	v_pk_mul_f32 v[22:23], v[22:23], v[30:31] op_sel:[0,1] op_sel_hi:[1,0]
	v_pk_mul_f32 v[16:17], v[16:17], v[24:25] op_sel:[0,1] op_sel_hi:[1,0]
	v_pk_mul_f32 v[18:19], v[18:19], v[26:27] op_sel:[0,1] op_sel_hi:[1,0]
	v_pk_mul_f32 v[20:21], v[20:21], v[144:145] op_sel_hi:[1,0]
	v_pk_mul_f32 v[22:23], v[22:23], v[146:147] op_sel_hi:[1,0]
	v_pk_mul_f32 v[16:17], v[16:17], v[148:149] op_sel_hi:[1,0]
	v_pk_mul_f32 v[18:19], v[18:19], v[150:151] op_sel_hi:[1,0]
	v_cvt_pk_bf16_f32 v28, v20, v21
	v_cvt_pk_bf16_f32 v29, v22, v23
	v_cvt_pk_bf16_f32 v30, v16, v17
	v_cvt_pk_bf16_f32 v31, v18, v19
	v_lshl_add_u64 v[178:179], v[176:177], 0, s[8:9]
	global_store_dwordx4 v[178:179], v[28:31], off
	v_pk_mul_f32 v[4:5], v[12:13], v[4:5]
	v_pk_mul_f32 v[6:7], v[14:15], v[6:7]
	v_pk_mul_f32 v[0:1], v[8:9], v[0:1]
	v_pk_mul_f32 v[2:3], v[10:11], v[2:3]
	s_waitcnt lgkmcnt(0)
	v_mov_b32_e32 v150, v175
	v_pk_mul_f32 v[12:13], v[12:13], v[150:151] op_sel_hi:[1,0]
	v_pk_mul_f32 v[14:15], v[14:15], v[150:151] op_sel_hi:[1,0]
	v_pk_mul_f32 v[8:9], v[8:9], v[150:151] op_sel_hi:[1,0]
	v_pk_mul_f32 v[10:11], v[10:11], v[150:151] op_sel_hi:[1,0]
	v_exp_f32_e32 v12, v12
	v_exp_f32_e32 v13, v13
	v_exp_f32_e32 v14, v14
	v_exp_f32_e32 v15, v15
	v_exp_f32_e32 v8, v8
	v_exp_f32_e32 v9, v9
	v_exp_f32_e32 v10, v10
	v_exp_f32_e32 v11, v11
	v_fma_f32 v12, v12, v174, v174
	v_fma_f32 v13, v13, v174, v174
	v_fma_f32 v14, v14, v174, v174
	v_fma_f32 v15, v15, v174, v174
	v_fma_f32 v8, v8, v174, v174
	v_fma_f32 v9, v9, v174, v174
	v_fma_f32 v10, v10, v174, v174
	v_fma_f32 v11, v11, v174, v174
	v_mul_f32_e32 v144, v12, v13
	v_mul_f32_e32 v146, v14, v15
	v_mul_f32_e32 v148, v8, v9
	v_mul_f32_e32 v150, v10, v11
	v_rcp_f32_e32 v144, v144
	v_rcp_f32_e32 v146, v146
	v_rcp_f32_e32 v148, v148
	v_rcp_f32_e32 v150, v150
	s_mov_b32 s8, 0xf2000
	v_pk_mul_f32 v[4:5], v[4:5], v[12:13] op_sel:[0,1] op_sel_hi:[1,0]
	v_pk_mul_f32 v[6:7], v[6:7], v[14:15] op_sel:[0,1] op_sel_hi:[1,0]
	v_pk_mul_f32 v[0:1], v[0:1], v[8:9] op_sel:[0,1] op_sel_hi:[1,0]
	v_pk_mul_f32 v[2:3], v[2:3], v[10:11] op_sel:[0,1] op_sel_hi:[1,0]
	v_pk_mul_f32 v[4:5], v[4:5], v[144:145] op_sel_hi:[1,0]
	v_pk_mul_f32 v[6:7], v[6:7], v[146:147] op_sel_hi:[1,0]
	v_pk_mul_f32 v[0:1], v[0:1], v[148:149] op_sel_hi:[1,0]
	v_pk_mul_f32 v[2:3], v[2:3], v[150:151] op_sel_hi:[1,0]
	v_cvt_pk_bf16_f32 v12, v4, v5
	v_cvt_pk_bf16_f32 v13, v6, v7
	v_cvt_pk_bf16_f32 v14, v0, v1
	v_cvt_pk_bf16_f32 v15, v2, v3
	v_lshl_add_u64 v[178:179], v[176:177], 0, s[8:9]
	global_store_dwordx4 v[178:179], v[12:15], off
	s_andn2_b64 vcc, exec, s[6:7]
	s_mov_b64 s[6:7], -1
	s_cbranch_vccnz .LBB0_1047
	s_andn2_b64 vcc, exec, s[12:13]
	s_cbranch_vccnz .LBB0_1046
	s_barrier
	s_branch .LBB0_1046
